# as v171 but the grid-barrier release poll loops spin without s_sleep (same code size)
# baseline (speedup 1.0000x reference)
.LBB0_191:
	s_and_b32 s18, s26, 0xff
	s_mov_b64 s[16:17], -1
	s_cmp_lg_u32 s18, 0
	s_mov_b64 s[18:19], -1
	s_nop 0
	s_cbranch_scc1 .LBB0_195
	v_mov_b64_e32 v[2:3], s[2:3]
	flat_load_dword v0, v[2:3] offset:512 sc1
	s_mov_b64 s[18:19], 0
	s_mov_b64 s[20:21], -1
	s_waitcnt vmcnt(0) lgkmcnt(0)
	v_cmp_eq_u32_e32 vcc, 0, v0
	s_and_saveexec_b64 s[22:23], vcc
	s_cmp_lt_u32 s26, 0x40001
	s_cselect_b64 s[18:19], -1, 0
	s_xor_b64 s[20:21], exec, -1
	s_and_b64 s[18:19], s[18:19], exec
	s_or_b64 exec, exec, s[22:23]
